# attention VALU diet only: XOR-derived K read bases and shortened lazy-rescale branch test on the folded GEMM early-barrier stack (no attention barrier rotation)
# speedup vs baseline: 1.0034x; 1.0034x over previous
.LBB0_185:
	s_waitcnt vmcnt(0)
	s_barrier
	v_mbcnt_lo_u32_b32 v192, -1, 0
	v_mbcnt_hi_u32_b32 v192, -1, v192
	s_add_i32 s35, 0, 0x10000
	s_add_i32 s37, s35, s61
	s_add_i32 s92, s37, 0x4000
	s_add_i32 s35, s35, s65
	s_add_i32 s93, s35, 0x4000
	s_add_u32 s98, s8, s14
	s_addc_u32 s99, s9, s15
	s_add_u32 s100, s8, s28
	s_addc_u32 s101, s9, s29
	s_add_i32 s36, s68, s79
	s_add_i32 s90, s36, 64
	s_add_i32 s34, s79, 63
	s_mul_hi_i32 s91, s90, 0xa000
	s_mul_i32 s90, s90, 0xa000
	s_add_u32 s90, s82, s90
	s_addc_u32 s91, s83, s91
	s_add_i32 s94, s47, s70
	s_add_i32 s95, s94, 0x380
	s_add_i32 s96, s47, s74
	s_add_i32 s97, s47, s77
	s_addk_i32 s97, 0xff80
	v_ashrrev_i32_e32 v188, 5, v192
	v_and_b32_e32 v193, 31, v192
	v_lshlrev_b32_e32 v189, 4, v192
	v_lshlrev_b32_e32 v191, 4, v188
	v_lshlrev_b32_e32 v190, 8, v193
	v_bitop3_b32 v2, v189, v191, s48 bitop3:0x6c
	v_add3_u32 v6, s84, v2, v190
	v_xor_b32_e32 v250, 32, v6
	v_xor_b32_e32 v222, 64, v6
	v_xor_b32_e32 v190, 0x60, v6
	v_add_u32_e32 v189, s81, v189
	ds_read_b128 v[2:5], v6
	ds_read_b128 v[194:197], v6 offset:8192
	ds_read_b128 v[198:201], v250
	ds_read_b128 v[202:205], v250 offset:8192
	ds_read_b128 v[206:209], v222
	ds_read_b128 v[210:213], v222 offset:8192
	ds_read_b128 v[214:217], v190
	ds_read_b128 v[218:221], v190 offset:8192
	ds_read_b128 v[226:229], v6 offset:128
	ds_read_b128 v[230:233], v6 offset:8320
	s_waitcnt lgkmcnt(9)
	s_mov_b32 m0, s37
	v_mfma_f32_32x32x16_bf16 v[18:33], v[2:5], v[34:37], 0
	global_load_lds_dwordx4 v251, s[98:99]
	s_waitcnt lgkmcnt(8)
	s_mov_b32 m0, s92
	v_mfma_f32_32x32x16_bf16 v[2:17], v[194:197], v[34:37], 0
	global_load_lds_dwordx4 v251, s[100:101]
	ds_read_b128 v[194:197], v250 offset:128
	s_waitcnt lgkmcnt(8)
	s_mov_b32 m0, s35
	v_mfma_f32_32x32x16_bf16 v[18:33], v[198:201], v[38:41], v[18:33]
	global_load_lds_dwordx4 v252, s[98:99]
	ds_read_b128 v[198:201], v250 offset:8320
	s_waitcnt lgkmcnt(8)
	s_mov_b32 m0, s93
	v_mfma_f32_32x32x16_bf16 v[2:17], v[202:205], v[38:41], v[2:17]
	global_load_lds_dwordx4 v252, s[100:101]
	ds_read_b128 v[202:205], v222 offset:128
	s_waitcnt lgkmcnt(8)
	s_mov_b32 m0, s94
	v_mfma_f32_32x32x16_bf16 v[18:33], v[206:209], v[42:45], v[18:33]
	global_load_lds_dwordx4 v253, s[90:91]
	ds_read_b128 v[206:209], v222 offset:8320
	s_waitcnt lgkmcnt(8)
	s_mov_b32 m0, s95
	v_mfma_f32_32x32x16_bf16 v[2:17], v[210:213], v[42:45], v[2:17]
	global_load_lds_dwordx4 v253, s[90:91] offset:128
	ds_read_b128 v[210:213], v190 offset:128
	s_waitcnt lgkmcnt(8)
	s_mov_b32 m0, s96
	v_mfma_f32_32x32x16_bf16 v[18:33], v[214:217], v[46:49], v[18:33]
	global_load_lds_dwordx4 v254, s[90:91]
	ds_read_b128 v[214:217], v190 offset:8320
	s_waitcnt lgkmcnt(8)
	s_mov_b32 m0, s97
	v_mfma_f32_32x32x16_bf16 v[2:17], v[218:221], v[46:49], v[2:17]
	global_load_lds_dwordx4 v254, s[90:91] offset:128
	ds_read_b128 v[218:221], v189
	s_waitcnt lgkmcnt(8)
	v_mfma_f32_32x32x16_bf16 v[18:33], v[226:229], v[50:53], v[18:33]
	ds_read_b128 v[226:229], v189 offset:1024
	s_waitcnt lgkmcnt(8)
	v_mfma_f32_32x32x16_bf16 v[2:17], v[230:233], v[50:53], v[2:17]
	s_waitcnt lgkmcnt(7)
	v_mfma_f32_32x32x16_bf16 v[18:33], v[194:197], v[54:57], v[18:33]
	s_waitcnt lgkmcnt(6)
	v_mfma_f32_32x32x16_bf16 v[2:17], v[198:201], v[54:57], v[2:17]
	s_waitcnt lgkmcnt(1)
	v_mfma_f32_32x32x16_bf16 v[18:33], v[202:205], v[218:221], v[18:33]
	v_mfma_f32_32x32x16_bf16 v[2:17], v[206:209], v[218:221], v[2:17]
	s_waitcnt lgkmcnt(0)
	v_mfma_f32_32x32x16_bf16 v[18:33], v[210:213], v[226:229], v[18:33]
	s_cmp_le_u32 s34, s59
	v_mfma_f32_32x32x16_bf16 v[2:17], v[214:217], v[226:229], v[2:17]
	s_cbranch_scc1 .LBB0_187
	v_lshlrev_b32_e32 v188, 2, v188
	v_sub_u32_e32 v188, v193, v188
	v_add_u32_e32 v188, s86, v188
	v_add_u32_e32 v189, 0x80000001, v188
	v_cmp_gt_u32_e32 vcc, s46, v189
	s_nop 4
	v_cndmask_b32_e32 v18, v225, v18, vcc
	v_cmp_lt_i32_e32 vcc, 31, v189
	s_nop 1
	v_cndmask_b32_e32 v2, v225, v2, vcc
	v_cmp_lt_i32_e32 vcc, 0, v189
	v_subrev_u32_e32 v189, 31, v188
	s_nop 0
	v_cndmask_b32_e32 v19, v225, v19, vcc
	v_cmp_lt_u32_e32 vcc, s49, v189
	v_subrev_u32_e32 v189, 32, v188
	s_nop 0
	v_cndmask_b32_e32 v3, v225, v3, vcc
	v_cmp_lt_u32_e32 vcc, s49, v188
	s_nop 1
	v_cndmask_b32_e32 v20, v225, v20, vcc
	v_cmp_lt_u32_e32 vcc, s49, v189
	v_add_u32_e32 v189, -1, v188
	s_nop 0
	v_cndmask_b32_e32 v4, v225, v4, vcc
	v_cmp_lt_u32_e32 vcc, s49, v189
	v_subrev_u32_e32 v189, 33, v188
	s_nop 0
	v_cndmask_b32_e32 v21, v225, v21, vcc
	v_cmp_lt_u32_e32 vcc, s49, v189
	v_add_u32_e32 v189, -6, v188
	s_nop 0
	v_cndmask_b32_e32 v5, v225, v5, vcc
	v_cmp_lt_u32_e32 vcc, s49, v189
	v_subrev_u32_e32 v189, 38, v188
	s_nop 0
	v_cndmask_b32_e32 v22, v225, v22, vcc
	v_cmp_lt_u32_e32 vcc, s49, v189
	v_add_u32_e32 v189, -7, v188
	s_nop 0
	v_cndmask_b32_e32 v6, v225, v6, vcc
	v_cmp_lt_u32_e32 vcc, s49, v189
	v_subrev_u32_e32 v189, 39, v188
	s_nop 0
	v_cndmask_b32_e32 v23, v225, v23, vcc
	v_cmp_lt_u32_e32 vcc, s49, v189
	v_add_u32_e32 v189, -8, v188
	s_nop 0
	v_cndmask_b32_e32 v7, v225, v7, vcc
	v_cmp_lt_u32_e32 vcc, s49, v189
	v_subrev_u32_e32 v189, 40, v188
	s_nop 0
	v_cndmask_b32_e32 v24, v225, v24, vcc
	v_cmp_lt_u32_e32 vcc, s49, v189
	v_add_u32_e32 v189, -9, v188
	s_nop 0
	v_cndmask_b32_e32 v8, v225, v8, vcc
	v_cmp_lt_u32_e32 vcc, s49, v189
	v_subrev_u32_e32 v189, 41, v188
	s_nop 0
	v_cndmask_b32_e32 v25, v225, v25, vcc
	v_cmp_lt_u32_e32 vcc, s49, v189
	v_add_u32_e32 v189, -14, v188
	s_nop 0
	v_cndmask_b32_e32 v9, v225, v9, vcc
	v_cmp_lt_u32_e32 vcc, s49, v189
	v_subrev_u32_e32 v189, 46, v188
	s_nop 0
	v_cndmask_b32_e32 v26, v225, v26, vcc
	v_cmp_lt_u32_e32 vcc, s49, v189
	v_add_u32_e32 v189, -15, v188
	s_nop 0
	v_cndmask_b32_e32 v10, v225, v10, vcc
	v_cmp_lt_u32_e32 vcc, s49, v189
	v_subrev_u32_e32 v189, 47, v188
	s_nop 0
	v_cndmask_b32_e32 v27, v225, v27, vcc
	v_cmp_lt_u32_e32 vcc, s49, v189
	v_add_u32_e32 v189, -16, v188
	s_nop 0
	v_cndmask_b32_e32 v11, v225, v11, vcc
	v_cmp_lt_u32_e32 vcc, s49, v189
	v_subrev_u32_e32 v189, 48, v188
	s_nop 0
	v_cndmask_b32_e32 v28, v225, v28, vcc
	v_cmp_lt_u32_e32 vcc, s49, v189
	v_subrev_u32_e32 v189, 17, v188
	s_nop 0
	v_cndmask_b32_e32 v12, v225, v12, vcc
	v_cmp_lt_u32_e32 vcc, s49, v189
	v_subrev_u32_e32 v189, 49, v188
	s_nop 0
	v_cndmask_b32_e32 v29, v225, v29, vcc
	v_cmp_lt_u32_e32 vcc, s49, v189
	v_subrev_u32_e32 v189, 22, v188
	s_nop 0
	v_cndmask_b32_e32 v13, v225, v13, vcc
	v_cmp_lt_u32_e32 vcc, s49, v189
	v_subrev_u32_e32 v189, 54, v188
	s_nop 0
	v_cndmask_b32_e32 v30, v225, v30, vcc
	v_cmp_lt_u32_e32 vcc, s49, v189
	v_subrev_u32_e32 v189, 23, v188
	s_nop 0
	v_cndmask_b32_e32 v14, v225, v14, vcc
	v_cmp_lt_u32_e32 vcc, s49, v189
	v_subrev_u32_e32 v189, 55, v188
	s_nop 0
	v_cndmask_b32_e32 v31, v225, v31, vcc
	v_cmp_lt_u32_e32 vcc, s49, v189
	v_subrev_u32_e32 v189, 24, v188
	s_nop 0
	v_cndmask_b32_e32 v15, v225, v15, vcc
	v_cmp_lt_u32_e32 vcc, s49, v189
	v_subrev_u32_e32 v189, 56, v188
	s_nop 0
	v_cndmask_b32_e32 v32, v225, v32, vcc
	v_cmp_lt_u32_e32 vcc, s49, v189
	v_subrev_u32_e32 v189, 25, v188
	v_subrev_u32_e32 v188, 57, v188
	v_cndmask_b32_e32 v16, v225, v16, vcc
	v_cmp_lt_u32_e32 vcc, s49, v189
	s_nop 1
	v_cndmask_b32_e32 v33, v225, v33, vcc
	v_cmp_lt_u32_e32 vcc, s49, v188
	s_nop 1
	v_cndmask_b32_e32 v17, v225, v17, vcc

.LBB0_192:
	s_cmp_lg_u32 0, -1
	s_cselect_b32 s34, 0, 0
	s_add_i32 s34, s34, 0x8000
	s_waitcnt lgkmcnt(0)
	v_add_u32_e32 v220, s34, v255
	v_xor_b32_e32 v221, 0x110, v220
	ds_read_b64_tr_b16 v[18:19], v220 offset:0
	ds_read_b64_tr_b16 v[20:21], v221 offset:0
	v_xor_b32_e32 v222, 32, v220
	ds_read_b64_tr_b16 v[22:23], v222 offset:0
	v_xor_b32_e32 v250, 32, v221
	ds_read_b64_tr_b16 v[24:25], v250 offset:0
	ds_read_b64_tr_b16 v[26:27], v220 offset:0x200
	ds_read_b64_tr_b16 v[28:29], v221 offset:0x200
	s_waitcnt lgkmcnt(4)
	v_permlane16_swap_b32_e32 v10, v14
	v_permlane16_swap_b32_e32 v11, v15
	v_permlane16_swap_b32_e32 v12, v16
	v_permlane16_swap_b32_e32 v13, v17
	v_permlane16_swap_b32_e32 v2, v6
	v_permlane16_swap_b32_e32 v3, v7
	v_permlane16_swap_b32_e32 v4, v8
	v_permlane16_swap_b32_e32 v5, v9
	v_mfma_f32_16x16x32_bf16 v[30:33], v[10:13], v[18:21], v[58:61]
	v_mfma_f32_16x16x32_bf16 v[18:21], v[14:17], v[18:21], v[178:181]
	ds_read_b64_tr_b16 v[58:59], v222 offset:0x200
	ds_read_b64_tr_b16 v[60:61], v250 offset:0x200
	s_waitcnt lgkmcnt(4)
	v_mfma_f32_16x16x32_bf16 v[62:65], v[10:13], v[22:25], v[62:65]
	v_mfma_f32_16x16x32_bf16 v[22:25], v[14:17], v[22:25], v[166:169]
	ds_read_b64_tr_b16 v[166:167], v220 offset:0x400
	ds_read_b64_tr_b16 v[168:169], v221 offset:0x400
	s_waitcnt lgkmcnt(4)
	v_mfma_f32_16x16x32_bf16 v[66:69], v[10:13], v[26:29], v[66:69]
	v_mfma_f32_16x16x32_bf16 v[26:29], v[14:17], v[26:29], v[162:165]
	ds_read_b64_tr_b16 v[162:163], v222 offset:0x400
	ds_read_b64_tr_b16 v[164:165], v250 offset:0x400
	s_waitcnt lgkmcnt(4)
	v_mfma_f32_16x16x32_bf16 v[70:73], v[10:13], v[58:61], v[70:73]
	v_mfma_f32_16x16x32_bf16 v[58:61], v[14:17], v[58:61], v[154:157]
	ds_read_b64_tr_b16 v[154:155], v220 offset:0x600
	ds_read_b64_tr_b16 v[156:157], v221 offset:0x600
	s_waitcnt lgkmcnt(4)
	v_mfma_f32_16x16x32_bf16 v[178:181], v[10:13], v[166:169], v[74:77]
	v_mfma_f32_16x16x32_bf16 v[150:153], v[14:17], v[166:169], v[150:153]
	ds_read_b64_tr_b16 v[74:75], v222 offset:0x600
	ds_read_b64_tr_b16 v[76:77], v250 offset:0x600
	s_waitcnt lgkmcnt(4)
	v_mfma_f32_16x16x32_bf16 v[166:169], v[10:13], v[162:165], v[82:85]
	v_mfma_f32_16x16x32_bf16 v[162:165], v[14:17], v[162:165], v[142:145]
	ds_read_b64_tr_b16 v[82:83], v220 offset:0x2000
	ds_read_b64_tr_b16 v[84:85], v221 offset:0x2000
	s_waitcnt lgkmcnt(4)
	v_mfma_f32_16x16x32_bf16 v[192:195], v[10:13], v[154:157], v[90:93]
	v_mfma_f32_16x16x32_bf16 v[154:157], v[14:17], v[154:157], v[138:141]
	ds_read_b64_tr_b16 v[90:91], v222 offset:0x2000
	ds_read_b64_tr_b16 v[92:93], v250 offset:0x2000
	s_waitcnt lgkmcnt(4)
	v_mfma_f32_16x16x32_bf16 v[196:199], v[10:13], v[74:77], v[98:101]
	v_mfma_f32_16x16x32_bf16 v[200:203], v[14:17], v[74:77], v[130:133]
	ds_read_b64_tr_b16 v[74:75], v220 offset:0x2200
	ds_read_b64_tr_b16 v[76:77], v221 offset:0x2200
	s_waitcnt lgkmcnt(4)
	v_mfma_f32_16x16x32_bf16 v[110:113], v[10:13], v[82:85], v[110:113]
	v_mfma_f32_16x16x32_bf16 v[126:129], v[14:17], v[82:85], v[126:129]
	ds_read_b64_tr_b16 v[82:83], v222 offset:0x2200
	ds_read_b64_tr_b16 v[84:85], v250 offset:0x2200
	s_waitcnt lgkmcnt(4)
	v_mfma_f32_16x16x32_bf16 v[122:125], v[10:13], v[90:93], v[122:125]
	v_mfma_f32_16x16x32_bf16 v[118:121], v[14:17], v[90:93], v[118:121]
	ds_read_b64_tr_b16 v[90:91], v220 offset:0x2400
	ds_read_b64_tr_b16 v[92:93], v221 offset:0x2400
	s_waitcnt lgkmcnt(4)
	v_mfma_f32_16x16x32_bf16 v[204:207], v[10:13], v[74:77], v[134:137]
	v_mfma_f32_16x16x32_bf16 v[208:211], v[14:17], v[74:77], v[114:117]
	ds_read_b64_tr_b16 v[74:75], v222 offset:0x2400
	ds_read_b64_tr_b16 v[76:77], v250 offset:0x2400
	s_waitcnt lgkmcnt(4)
	v_mfma_f32_16x16x32_bf16 v[212:215], v[10:13], v[82:85], v[146:149]
	v_mfma_f32_16x16x32_bf16 v[216:219], v[14:17], v[82:85], v[106:109]
	ds_read_b64_tr_b16 v[82:83], v220 offset:0x2600
	ds_read_b64_tr_b16 v[84:85], v221 offset:0x2600
	s_waitcnt lgkmcnt(4)
	v_mfma_f32_16x16x32_bf16 v[226:229], v[10:13], v[90:93], v[158:161]
	v_mfma_f32_16x16x32_bf16 v[230:233], v[14:17], v[90:93], v[102:105]
	ds_read_b64_tr_b16 v[90:91], v222 offset:0x2600
	ds_read_b64_tr_b16 v[92:93], v250 offset:0x2600
	s_waitcnt lgkmcnt(4)
	v_mfma_f32_16x16x32_bf16 v[234:237], v[10:13], v[74:77], v[174:177]
	v_mfma_f32_16x16x32_bf16 v[238:241], v[14:17], v[74:77], v[94:97]
	ds_read_b64_tr_b16 v[94:95], v220 offset:0x4000
	ds_read_b64_tr_b16 v[96:97], v221 offset:0x4000
	s_waitcnt lgkmcnt(4)
	v_mfma_f32_16x16x32_bf16 v[242:245], v[10:13], v[82:85], v[182:185]
	v_mfma_f32_16x16x32_bf16 v[246:249], v[14:17], v[82:85], v[86:89]
	ds_read_b64_tr_b16 v[82:83], v222 offset:0x4000
	ds_read_b64_tr_b16 v[84:85], v250 offset:0x4000
	s_waitcnt lgkmcnt(4)
	v_mfma_f32_16x16x32_bf16 v[10:13], v[10:13], v[90:93], v[170:173]
	v_mfma_f32_16x16x32_bf16 v[14:17], v[14:17], v[90:93], v[78:81]
	ds_read_b64_tr_b16 v[86:87], v220 offset:0x4200
	ds_read_b64_tr_b16 v[88:89], v221 offset:0x4200
	s_waitcnt lgkmcnt(4)
	v_mfma_f32_16x16x32_bf16 v[74:77], v[2:5], v[94:97], v[30:33]
	v_mfma_f32_16x16x32_bf16 v[130:133], v[6:9], v[94:97], v[18:21]
	ds_read_b64_tr_b16 v[18:19], v222 offset:0x4200
	ds_read_b64_tr_b16 v[20:21], v250 offset:0x4200
	s_waitcnt lgkmcnt(4)
	v_mfma_f32_16x16x32_bf16 v[78:81], v[2:5], v[82:85], v[62:65]
	v_mfma_f32_16x16x32_bf16 v[134:137], v[6:9], v[82:85], v[22:25]
	ds_read_b64_tr_b16 v[22:23], v220 offset:0x4400
	ds_read_b64_tr_b16 v[24:25], v221 offset:0x4400
	s_waitcnt lgkmcnt(4)
	v_mfma_f32_16x16x32_bf16 v[82:85], v[2:5], v[86:89], v[66:69]
	v_mfma_f32_16x16x32_bf16 v[138:141], v[6:9], v[86:89], v[26:29]
	ds_read_b64_tr_b16 v[26:27], v222 offset:0x4400
	ds_read_b64_tr_b16 v[28:29], v250 offset:0x4400
	s_waitcnt lgkmcnt(4)
	v_mfma_f32_16x16x32_bf16 v[86:89], v[2:5], v[18:21], v[70:73]
	v_mfma_f32_16x16x32_bf16 v[142:145], v[6:9], v[18:21], v[58:61]
	ds_read_b64_tr_b16 v[18:19], v220 offset:0x4600
	ds_read_b64_tr_b16 v[20:21], v221 offset:0x4600
	s_waitcnt lgkmcnt(4)
	v_mfma_f32_16x16x32_bf16 v[90:93], v[2:5], v[22:25], v[178:181]
	v_mfma_f32_16x16x32_bf16 v[146:149], v[6:9], v[22:25], v[150:153]
	ds_read_b64_tr_b16 v[22:23], v222 offset:0x4600
	ds_read_b64_tr_b16 v[24:25], v250 offset:0x4600
	s_waitcnt lgkmcnt(4)
	v_mfma_f32_16x16x32_bf16 v[94:97], v[2:5], v[26:29], v[166:169]
	v_mfma_f32_16x16x32_bf16 v[150:153], v[6:9], v[26:29], v[162:165]
	ds_read_b64_tr_b16 v[26:27], v220 offset:0x6000
	ds_read_b64_tr_b16 v[28:29], v221 offset:0x6000
	s_waitcnt lgkmcnt(4)
	v_mfma_f32_16x16x32_bf16 v[98:101], v[2:5], v[18:21], v[192:195]
	v_mfma_f32_16x16x32_bf16 v[154:157], v[6:9], v[18:21], v[154:157]
	ds_read_b64_tr_b16 v[18:19], v222 offset:0x6000
	ds_read_b64_tr_b16 v[20:21], v250 offset:0x6000
	s_waitcnt lgkmcnt(4)
	v_mfma_f32_16x16x32_bf16 v[102:105], v[2:5], v[22:25], v[196:199]
	v_mfma_f32_16x16x32_bf16 v[158:161], v[6:9], v[22:25], v[200:203]
	ds_read_b64_tr_b16 v[22:23], v220 offset:0x6200
	ds_read_b64_tr_b16 v[24:25], v221 offset:0x6200
	s_waitcnt lgkmcnt(4)
	v_mfma_f32_16x16x32_bf16 v[106:109], v[2:5], v[26:29], v[110:113]
	v_mfma_f32_16x16x32_bf16 v[162:165], v[6:9], v[26:29], v[126:129]
	ds_read_b64_tr_b16 v[26:27], v222 offset:0x6200
	ds_read_b64_tr_b16 v[28:29], v250 offset:0x6200
	s_waitcnt lgkmcnt(4)
	v_mfma_f32_16x16x32_bf16 v[110:113], v[2:5], v[18:21], v[122:125]
	v_mfma_f32_16x16x32_bf16 v[166:169], v[6:9], v[18:21], v[118:121]
	ds_read_b64_tr_b16 v[18:19], v220 offset:0x6400
	ds_read_b64_tr_b16 v[20:21], v221 offset:0x6400
	s_waitcnt lgkmcnt(4)
	v_mfma_f32_16x16x32_bf16 v[114:117], v[2:5], v[22:25], v[204:207]
	v_mfma_f32_16x16x32_bf16 v[170:173], v[6:9], v[22:25], v[208:211]
	ds_read_b64_tr_b16 v[22:23], v222 offset:0x6400
	ds_read_b64_tr_b16 v[24:25], v250 offset:0x6400
	s_waitcnt lgkmcnt(4)
	v_mfma_f32_16x16x32_bf16 v[118:121], v[2:5], v[26:29], v[212:215]
	v_mfma_f32_16x16x32_bf16 v[174:177], v[6:9], v[26:29], v[216:219]
	ds_read_b64_tr_b16 v[26:27], v220 offset:0x6600
	ds_read_b64_tr_b16 v[28:29], v221 offset:0x6600
	s_waitcnt lgkmcnt(4)
	v_mfma_f32_16x16x32_bf16 v[122:125], v[2:5], v[18:21], v[226:229]
	v_mfma_f32_16x16x32_bf16 v[178:181], v[6:9], v[18:21], v[230:233]
	ds_read_b64_tr_b16 v[18:19], v222 offset:0x6600
	ds_read_b64_tr_b16 v[20:21], v250 offset:0x6600
	s_waitcnt lgkmcnt(4)
	v_mfma_f32_16x16x32_bf16 v[126:129], v[2:5], v[22:25], v[234:237]
	v_mfma_f32_16x16x32_bf16 v[182:185], v[6:9], v[22:25], v[238:241]
	s_waitcnt lgkmcnt(2)
	v_mfma_f32_16x16x32_bf16 v[66:69], v[2:5], v[26:29], v[242:245]
	v_mfma_f32_16x16x32_bf16 v[70:73], v[6:9], v[26:29], v[246:249]
	s_waitcnt lgkmcnt(0)
	v_mfma_f32_16x16x32_bf16 v[58:61], v[2:5], v[18:21], v[10:13]
	v_mfma_f32_16x16x32_bf16 v[62:65], v[6:9], v[18:21], v[14:17]
	s_cmp_ge_u32 s89, s80
	s_waitcnt vmcnt(0)
	s_barrier
	s_cselect_b64 s[34:35], -1, 0
	s_and_b64 vcc, exec, s[34:35]
	v_mbcnt_lo_u32_b32 v192, -1, 0
	v_mbcnt_hi_u32_b32 v192, -1, v192
	s_cbranch_vccnz .LBB0_194
	s_add_u32 s98, s8, s30
	s_addc_u32 s99, s9, s31
	s_addk_i32 s36, 0x80
	s_mul_hi_i32 s37, s36, 0xa000
	s_mul_i32 s36, s36, 0xa000
	s_add_u32 s36, s82, s36
	s_addc_u32 s37, s83, s37
	s_add_i32 s100, s72, 0xffffff80
	s_add_i32 s101, s78, 0xffffff80
	v_ashrrev_i32_e32 v193, 5, v192
	v_and_b32_e32 v194, 31, v192
	v_lshlrev_b32_e32 v195, 4, v192
	v_lshlrev_b32_e32 v221, 4, v193
	v_lshlrev_b32_e32 v220, 8, v194
	v_bitop3_b32 v2, v195, v221, s48 bitop3:0x6c
	v_add3_u32 v6, s85, v2, v220
	v_xor_b32_e32 v250, 32, v6
	v_xor_b32_e32 v222, 64, v6
	v_xor_b32_e32 v220, 0x60, v6
	v_add_u32_e32 v195, s81, v195
	ds_read_b128 v[2:5], v6
	ds_read_b128 v[196:199], v6 offset:8192
	ds_read_b128 v[200:203], v250
	ds_read_b128 v[204:207], v250 offset:8192
	ds_read_b128 v[208:211], v222
	ds_read_b128 v[212:215], v222 offset:8192
	ds_read_b128 v[216:219], v220
	ds_read_b128 v[226:229], v220 offset:8192
	ds_read_b128 v[230:233], v6 offset:128
	ds_read_b128 v[234:237], v6 offset:8320
	s_waitcnt lgkmcnt(9)
	s_mov_b32 m0, s62
	v_mfma_f32_32x32x16_bf16 v[18:33], v[2:5], v[34:37], 0
	global_load_lds_dwordx4 v251, s[98:99]
	s_waitcnt lgkmcnt(8)
	s_mov_b32 m0, s63
	v_mfma_f32_32x32x16_bf16 v[2:17], v[196:199], v[34:37], 0
	global_load_lds_dwordx4 v251, s[8:9]
	ds_read_b128 v[196:199], v250 offset:128
	s_waitcnt lgkmcnt(8)
	s_mov_b32 m0, s66
	v_mfma_f32_32x32x16_bf16 v[18:33], v[200:203], v[38:41], v[18:33]
	global_load_lds_dwordx4 v252, s[98:99]
	ds_read_b128 v[200:203], v250 offset:8320
	s_waitcnt lgkmcnt(8)
	s_mov_b32 m0, s67
	v_mfma_f32_32x32x16_bf16 v[2:17], v[204:207], v[38:41], v[2:17]
	global_load_lds_dwordx4 v252, s[8:9]
	ds_read_b128 v[204:207], v222 offset:128
	s_waitcnt lgkmcnt(8)
	s_mov_b32 m0, s71
	v_mfma_f32_32x32x16_bf16 v[18:33], v[208:211], v[42:45], v[18:33]
	global_load_lds_dwordx4 v253, s[36:37]
	ds_read_b128 v[208:211], v222 offset:8320
	s_waitcnt lgkmcnt(8)
	s_mov_b32 m0, s100
	v_mfma_f32_32x32x16_bf16 v[2:17], v[212:215], v[42:45], v[2:17]
	global_load_lds_dwordx4 v253, s[36:37] offset:128
	ds_read_b128 v[212:215], v220 offset:128
	s_waitcnt lgkmcnt(8)
	s_mov_b32 m0, s75
	v_mfma_f32_32x32x16_bf16 v[18:33], v[216:219], v[46:49], v[18:33]
	global_load_lds_dwordx4 v254, s[36:37]
	ds_read_b128 v[216:219], v220 offset:8320
	s_waitcnt lgkmcnt(8)
	s_mov_b32 m0, s101
	v_mfma_f32_32x32x16_bf16 v[2:17], v[226:229], v[46:49], v[2:17]
	global_load_lds_dwordx4 v254, s[36:37] offset:128
	ds_read_b128 v[226:229], v195
	s_waitcnt lgkmcnt(8)
	v_mfma_f32_32x32x16_bf16 v[18:33], v[230:233], v[50:53], v[18:33]
	ds_read_b128 v[230:233], v195 offset:1024
	s_waitcnt lgkmcnt(8)
	v_mfma_f32_32x32x16_bf16 v[2:17], v[234:237], v[50:53], v[2:17]
	s_waitcnt lgkmcnt(7)
	v_mfma_f32_32x32x16_bf16 v[18:33], v[196:199], v[54:57], v[18:33]
	s_waitcnt lgkmcnt(6)
	v_mfma_f32_32x32x16_bf16 v[2:17], v[200:203], v[54:57], v[2:17]
	s_waitcnt lgkmcnt(1)
	v_mfma_f32_32x32x16_bf16 v[18:33], v[204:207], v[226:229], v[18:33]
	v_mfma_f32_32x32x16_bf16 v[2:17], v[208:211], v[226:229], v[2:17]
	s_waitcnt lgkmcnt(0)
	v_mfma_f32_32x32x16_bf16 v[18:33], v[212:215], v[230:233], v[18:33]
	s_add_i32 s36, s79, 0x7f
	s_cmp_le_u32 s36, s59
	v_mfma_f32_32x32x16_bf16 v[2:17], v[216:219], v[230:233], v[2:17]
	s_branch .Lqk1_join
